# v71 + touch xres/ga lines of the residual epilogues (out-proj, down) during the last K iteration
# baseline (speedup 1.0000x reference)
; #define PG8_STAGE(bufoff, gbase, voff) do { _Pragma("unroll") for (int _i = 0; _i < 2; ++_i) \
;         __builtin_amdgcn_global_load_lds((const unsigned*)((const char*)(gbase) + (voff)[_i]), (PG8_LAS unsigned*)(lds + (bufoff) + ldsw + _i * 8192), 16, 0, 0); } while (0)
; #define PG8_LDA(dst, b, h) do { _Pragma("unroll") for (int m = 0; m < 4; ++m) _Pragma("unroll") for (int k = 0; k < 2; ++k) dst[m][k] = *(const PG8_LAS bf16x8*)(lds + PG8_SA(b, h) + aoff + m * 2048 + k * 1024); } while (0)
; #define PG8_LDB(dst, b, h) do { _Pragma("unroll") for (int n = 0; n < 2; ++n) _Pragma("unroll") for (int k = 0; k < 2; ++k) dst[n][k] = *(const PG8_LAS bf16x8*)(lds + PG8_SB(b, h) + boff + n * 2048 + k * 1024); } while (0)
; #define PG8_MMA(ai, bj, At, Bt) do { __builtin_amdgcn_s_setprio(1); _Pragma("unroll") for (int m = 0; m < 4; ++m) _Pragma("unroll") for (int n = 0; n < 2; ++n) _Pragma("unroll") for (int k = 0; k < 2; ++k) \
;         acc[ai][bj][m][n] = __builtin_amdgcn_mfma_f32_16x16x32_bf16(Bt[n][k], At[m][k], acc[ai][bj][m][n], 0, 0, 0); __builtin_amdgcn_s_setprio(0); } while (0)
; #define PG8_WAIT_V(n) asm volatile("s_waitcnt vmcnt(" #n ")" ::: "memory")
; #define PG8_WAIT_L(n) asm volatile("s_waitcnt lgkmcnt(" #n ")" ::: "memory")
; #define PG8_BAR __builtin_amdgcn_s_barrier()
; template <class Epi, class Sched, bool ALIGN_EPI = false, bool SP2 = false, bool ATILED = false, bool BTILED = false>
; __device__ __forceinline__ void gemm_phase(PG8_LAS unsigned char* lds, const Gemm g, const Sched& S, const Epi& E, const int tid) {
;     ...
;             const bool last = (t == nt - 2);
;             const char* a1 = cA + (size_t)(t + 1) * kstepA;
;             const char* a2 = last ? nA : cA + (size_t)(t + 2) * kstepA; const char* b2 = last ? nB : cB + (size_t)(t + 2) * kstepB;
;             const char* a3 = a2 + kstepA; const char* b3 = b2 + kstepB;
;             if (last && has_next) S.a_ready(nxt);
;             if constexpr (SP2) {
;             PG8_LDB(B0, 0, 0); PG8_LDB(B1, 0, 1); PG8_SCHED; PG8_LDA(At, 0, 0); PG8_STAGE(PG8_SA(1, 1), a1 + hstepA, voffA);
;             PG8_WAIT_V(8); PG8_WAIT_L(0); PG8_BAR; PG8_MMA(0, 0, At, B0); PG8_MMA(0, 1, At, B1); PG8_BAR; PG8_SCHED;
;             PG8_LDA(At, 0, 1); PG8_STAGE(PG8_SB(0, 0), b2, voffB); PG8_STAGE(PG8_SB(0, 1), b2 + hstepB, voffB); PG8_STAGE(PG8_SA(0, 0), a2, voffA);
.LBB0_233:
	s_add_u32 s52, s28, 0x4000
	s_addc_u32 s53, s29, 0
	s_cmp_eq_u32 s72, 12
	s_cselect_b32 s56, s18, s52
	s_cselect_b32 s57, s11, s53
	s_cselect_b32 s54, s19, s25
	s_cselect_b32 s55, s9, s27
	s_add_u32 s52, s56, 0x8000
	s_addc_u32 s53, s57, 0
	s_add_i32 s73, 0, 0x10000
	s_add_i32 s76, 0, 0x14000
	v_add_u32_e32 v142, s73, v177
	v_add_u32_e32 v170, s76, v177
	ds_read_b128 v[130:133], v142
	ds_read_b128 v[134:137], v142 offset:1024
	ds_read_b128 v[138:141], v142 offset:2048
	ds_read_b128 v[142:145], v142 offset:3072
	ds_read_b128 v[146:149], v170
	ds_read_b128 v[162:165], v170 offset:1024
	ds_read_b128 v[166:169], v170 offset:2048
	ds_read_b128 v[170:173], v170 offset:3072
	v_lshl_add_u64 v[174:175], s[28:29], 0, v[158:159]
	s_add_i32 m0, s62, 0xc000
	ds_read_b128 v[180:183], v186
	ds_read_b128 v[188:191], v186 offset:1024
	ds_read_b128 v[196:199], v186 offset:2048
	ds_read_b128 v[200:203], v186 offset:3072
	ds_read_b128 v[204:207], v186 offset:4096
	ds_read_b128 v[208:211], v186 offset:5120
	ds_read_b128 v[212:215], v186 offset:6144
	ds_read_b128 v[216:219], v186 offset:7168
	global_load_lds_dwordx4 v[174:175], off
	v_lshl_add_u64 v[174:175], s[28:29], 0, v[160:161]
	s_add_i32 m0, s62, 0xe000
	s_nop 0
	global_load_lds_dwordx4 v[174:175], off
	s_waitcnt vmcnt(8)
	s_waitcnt lgkmcnt(0)
	s_barrier
	s_setprio 1
	s_waitcnt lgkmcnt(0)
	v_mfma_f32_16x16x32_bf16 v[126:129], v[130:133], v[180:183], v[126:129]
	v_mfma_f32_16x16x32_bf16 v[122:125], v[138:141], v[180:183], v[122:125]
	v_mfma_f32_16x16x32_bf16 v[118:121], v[130:133], v[196:199], v[118:121]
	v_mfma_f32_16x16x32_bf16 v[114:117], v[138:141], v[196:199], v[114:117]
	v_mfma_f32_16x16x32_bf16 v[110:113], v[130:133], v[204:207], v[110:113]
	v_mfma_f32_16x16x32_bf16 v[106:109], v[138:141], v[204:207], v[106:109]
	v_mfma_f32_16x16x32_bf16 v[102:105], v[130:133], v[212:215], v[102:105]
	v_mfma_f32_16x16x32_bf16 v[98:101], v[138:141], v[212:215], v[98:101]
	v_mfma_f32_16x16x32_bf16 v[126:129], v[134:137], v[188:191], v[126:129]
	v_mfma_f32_16x16x32_bf16 v[122:125], v[142:145], v[188:191], v[122:125]
	v_mfma_f32_16x16x32_bf16 v[118:121], v[134:137], v[200:203], v[118:121]
	v_mfma_f32_16x16x32_bf16 v[114:117], v[142:145], v[200:203], v[114:117]
	v_mfma_f32_16x16x32_bf16 v[110:113], v[134:137], v[208:211], v[110:113]
	v_mfma_f32_16x16x32_bf16 v[106:109], v[142:145], v[208:211], v[106:109]
	v_mfma_f32_16x16x32_bf16 v[102:105], v[134:137], v[216:219], v[102:105]
	v_mfma_f32_16x16x32_bf16 v[98:101], v[142:145], v[216:219], v[98:101]
	s_setprio 0
	s_setprio 1
	v_mfma_f32_16x16x32_bf16 v[94:97], v[146:149], v[180:183], v[94:97]
	v_mfma_f32_16x16x32_bf16 v[90:93], v[166:169], v[180:183], v[90:93]
	v_mfma_f32_16x16x32_bf16 v[86:89], v[146:149], v[196:199], v[86:89]
	v_mfma_f32_16x16x32_bf16 v[82:85], v[166:169], v[196:199], v[82:85]
	v_mfma_f32_16x16x32_bf16 v[78:81], v[146:149], v[204:207], v[78:81]
	v_mfma_f32_16x16x32_bf16 v[74:77], v[166:169], v[204:207], v[74:77]
	v_mfma_f32_16x16x32_bf16 v[70:73], v[146:149], v[212:215], v[70:73]
	v_mfma_f32_16x16x32_bf16 v[66:69], v[166:169], v[212:215], v[66:69]
	v_mfma_f32_16x16x32_bf16 v[94:97], v[162:165], v[188:191], v[94:97]
	v_mfma_f32_16x16x32_bf16 v[90:93], v[170:173], v[188:191], v[90:93]
	v_mfma_f32_16x16x32_bf16 v[86:89], v[162:165], v[200:203], v[86:89]
	v_mfma_f32_16x16x32_bf16 v[82:85], v[170:173], v[200:203], v[82:85]
	v_mfma_f32_16x16x32_bf16 v[78:81], v[162:165], v[208:211], v[78:81]
	v_mfma_f32_16x16x32_bf16 v[74:77], v[170:173], v[208:211], v[74:77]
	v_mfma_f32_16x16x32_bf16 v[70:73], v[162:165], v[216:219], v[70:73]
	v_mfma_f32_16x16x32_bf16 v[66:69], v[170:173], v[216:219], v[66:69]
	s_setprio 0
	s_barrier
	s_add_i32 s73, s73, s61
	v_lshl_add_u64 v[174:175], s[54:55], 0, v[152:153]
	s_mov_b32 m0, s73
	ds_read_b128 v[180:183], v186 offset:16384
	ds_read_b128 v[188:191], v186 offset:17408
	ds_read_b128 v[196:199], v186 offset:18432
	ds_read_b128 v[200:203], v186 offset:19456
	ds_read_b128 v[204:207], v186 offset:20480
	ds_read_b128 v[208:211], v186 offset:21504
	ds_read_b128 v[212:215], v186 offset:22528
	ds_read_b128 v[216:219], v186 offset:23552
	global_load_lds_dwordx4 v[174:175], off
	s_add_i32 m0, s73, 0x2000
	s_add_u32 s74, s54, 0x4000
	v_lshl_add_u64 v[174:175], s[54:55], 0, v[156:157]
	s_addc_u32 s75, s55, 0
	s_add_i32 s73, s76, s61
	global_load_lds_dwordx4 v[174:175], off
	v_lshl_add_u64 v[174:175], s[74:75], 0, v[152:153]
	s_mov_b32 m0, s73
	s_nop 0
	global_load_lds_dwordx4 v[174:175], off
	v_lshl_add_u64 v[174:175], s[74:75], 0, v[156:157]
	s_add_i32 m0, s73, 0x2000
	s_nop 0
	global_load_lds_dwordx4 v[174:175], off
	v_lshl_add_u64 v[174:175], s[56:57], 0, v[150:151]
	s_mov_b32 m0, s62
	s_nop 0
	global_load_lds_dwordx4 v[174:175], off
	v_lshl_add_u64 v[174:175], s[56:57], 0, v[154:155]
	s_mov_b32 m0, s63
	s_nop 0
	global_load_lds_dwordx4 v[174:175], off
	s_waitcnt vmcnt(8)
	s_waitcnt lgkmcnt(0)
	s_barrier
; #define PG8_STAGE(bufoff, gbase, voff) do { _Pragma("unroll") for (int _i = 0; _i < 2; ++_i) \
;         __builtin_amdgcn_global_load_lds((const unsigned*)((const char*)(gbase) + (voff)[_i]), (PG8_LAS unsigned*)(lds + (bufoff) + ldsw + _i * 8192), 16, 0, 0); } while (0)
; #define PG8_LDA(dst, b, h) do { _Pragma("unroll") for (int m = 0; m < 4; ++m) _Pragma("unroll") for (int k = 0; k < 2; ++k) dst[m][k] = *(const PG8_LAS bf16x8*)(lds + PG8_SA(b, h) + aoff + m * 2048 + k * 1024); } while (0)
; #define PG8_LDB(dst, b, h) do { _Pragma("unroll") for (int n = 0; n < 2; ++n) _Pragma("unroll") for (int k = 0; k < 2; ++k) dst[n][k] = *(const PG8_LAS bf16x8*)(lds + PG8_SB(b, h) + boff + n * 2048 + k * 1024); } while (0)
; #define PG8_MMA(ai, bj, At, Bt) do { __builtin_amdgcn_s_setprio(1); _Pragma("unroll") for (int m = 0; m < 4; ++m) _Pragma("unroll") for (int n = 0; n < 2; ++n) _Pragma("unroll") for (int k = 0; k < 2; ++k) \
;         acc[ai][bj][m][n] = __builtin_amdgcn_mfma_f32_16x16x32_bf16(Bt[n][k], At[m][k], acc[ai][bj][m][n], 0, 0, 0); __builtin_amdgcn_s_setprio(0); } while (0)
; #define PG8_WAIT_V(n) asm volatile("s_waitcnt vmcnt(" #n ")" ::: "memory")
; #define PG8_WAIT_L(n) asm volatile("s_waitcnt lgkmcnt(" #n ")" ::: "memory")
; #define PG8_BAR __builtin_amdgcn_s_barrier()
; #define PG8_SCHED __builtin_amdgcn_sched_barrier(0)
; template <class Epi, class Sched, bool ALIGN_EPI = false, bool SP2 = false, bool ATILED = false, bool BTILED = false>
; __device__ __forceinline__ void gemm_phase(PG8_LAS unsigned char* lds, const Gemm g, const Sched& S, const Epi& E, const int tid) {
;     ...
;             PG8_WAIT_V(8); PG8_WAIT_L(0); PG8_BAR; PG8_MMA(1, 0, At, B0); PG8_MMA(1, 1, At, B1); PG8_BAR; PG8_SCHED;
;             PG8_LDB(B0, 1, 0); PG8_LDB(B1, 1, 1); PG8_SCHED; PG8_LDA(At, 1, 0); PG8_STAGE(PG8_SA(0, 1), a2 + hstepA, voffA);
;             PG8_WAIT_V(8); PG8_WAIT_L(0); PG8_BAR; PG8_MMA(0, 0, At, B0); PG8_MMA(0, 1, At, B1); PG8_BAR; PG8_SCHED;
	s_setprio 1
	s_waitcnt lgkmcnt(0)
	v_mfma_f32_16x16x32_bf16 v[62:65], v[130:133], v[180:183], v[62:65]
	v_mfma_f32_16x16x32_bf16 v[58:61], v[138:141], v[180:183], v[58:61]
	v_mfma_f32_16x16x32_bf16 v[54:57], v[130:133], v[196:199], v[54:57]
	v_mfma_f32_16x16x32_bf16 v[50:53], v[138:141], v[196:199], v[50:53]
	v_mfma_f32_16x16x32_bf16 v[46:49], v[130:133], v[204:207], v[46:49]
	v_mfma_f32_16x16x32_bf16 v[42:45], v[138:141], v[204:207], v[42:45]
	v_mfma_f32_16x16x32_bf16 v[38:41], v[130:133], v[212:215], v[38:41]
	v_mfma_f32_16x16x32_bf16 v[34:37], v[138:141], v[212:215], v[34:37]
	v_mfma_f32_16x16x32_bf16 v[62:65], v[134:137], v[188:191], v[62:65]
	v_mfma_f32_16x16x32_bf16 v[58:61], v[142:145], v[188:191], v[58:61]
	v_mfma_f32_16x16x32_bf16 v[54:57], v[134:137], v[200:203], v[54:57]
	v_mfma_f32_16x16x32_bf16 v[50:53], v[142:145], v[200:203], v[50:53]
	v_mfma_f32_16x16x32_bf16 v[46:49], v[134:137], v[208:211], v[46:49]
	v_mfma_f32_16x16x32_bf16 v[42:45], v[142:145], v[208:211], v[42:45]
	v_mfma_f32_16x16x32_bf16 v[38:41], v[134:137], v[216:219], v[38:41]
	v_mfma_f32_16x16x32_bf16 v[34:37], v[142:145], v[216:219], v[34:37]
	s_setprio 0
	s_setprio 1
	v_mfma_f32_16x16x32_bf16 v[30:33], v[146:149], v[180:183], v[30:33]
	v_mfma_f32_16x16x32_bf16 v[26:29], v[166:169], v[180:183], v[26:29]
	v_mfma_f32_16x16x32_bf16 v[22:25], v[146:149], v[196:199], v[22:25]
	v_mfma_f32_16x16x32_bf16 v[18:21], v[166:169], v[196:199], v[18:21]
	v_mfma_f32_16x16x32_bf16 v[14:17], v[146:149], v[204:207], v[14:17]
	v_mfma_f32_16x16x32_bf16 v[10:13], v[166:169], v[204:207], v[10:13]
	v_mfma_f32_16x16x32_bf16 v[6:9], v[146:149], v[212:215], v[6:9]
	v_mfma_f32_16x16x32_bf16 v[2:5], v[166:169], v[212:215], v[2:5]
	v_mfma_f32_16x16x32_bf16 v[30:33], v[162:165], v[188:191], v[30:33]
	v_mfma_f32_16x16x32_bf16 v[26:29], v[170:173], v[188:191], v[26:29]
	v_mfma_f32_16x16x32_bf16 v[22:25], v[162:165], v[200:203], v[22:25]
	v_mfma_f32_16x16x32_bf16 v[18:21], v[170:173], v[200:203], v[18:21]
	v_mfma_f32_16x16x32_bf16 v[14:17], v[162:165], v[208:211], v[14:17]
	v_mfma_f32_16x16x32_bf16 v[10:13], v[170:173], v[208:211], v[10:13]
	v_mfma_f32_16x16x32_bf16 v[6:9], v[162:165], v[216:219], v[6:9]
	v_mfma_f32_16x16x32_bf16 v[2:5], v[170:173], v[216:219], v[2:5]
	s_setprio 0
	s_barrier
	s_add_i32 s73, 0, 0x18000
	s_add_i32 s74, 0, 0x1c000
	v_add_u32_e32 v142, s73, v177
	v_add_u32_e32 v170, s74, v177
	ds_read_b128 v[130:133], v142
	ds_read_b128 v[134:137], v142 offset:1024
	ds_read_b128 v[138:141], v142 offset:2048
	ds_read_b128 v[142:145], v142 offset:3072
	ds_read_b128 v[146:149], v170
	ds_read_b128 v[162:165], v170 offset:1024
	ds_read_b128 v[166:169], v170 offset:2048
	ds_read_b128 v[170:173], v170 offset:3072
	s_add_u32 s56, s56, 0x4000
	s_addc_u32 s57, s57, 0
	s_mov_b32 m0, s64
	v_lshl_add_u64 v[174:175], s[56:57], 0, v[150:151]
	ds_read_b128 v[180:183], v186 offset:32768
	ds_read_b128 v[188:191], v186 offset:33792
	ds_read_b128 v[196:199], v186 offset:34816
	ds_read_b128 v[200:203], v186 offset:35840
	ds_read_b128 v[204:207], v186 offset:36864
	ds_read_b128 v[208:211], v186 offset:37888
	ds_read_b128 v[212:215], v186 offset:38912
	ds_read_b128 v[216:219], v186 offset:39936
	global_load_lds_dwordx4 v[174:175], off
	v_lshl_add_u64 v[174:175], s[56:57], 0, v[154:155]
	s_mov_b32 m0, s65
	s_nop 0
	global_load_lds_dwordx4 v[174:175], off
	s_waitcnt vmcnt(8)
	s_waitcnt lgkmcnt(0)
	s_barrier
	s_setprio 1
	s_waitcnt lgkmcnt(0)
	v_mfma_f32_16x16x32_bf16 v[126:129], v[130:133], v[180:183], v[126:129]
	v_mfma_f32_16x16x32_bf16 v[122:125], v[138:141], v[180:183], v[122:125]
	v_mfma_f32_16x16x32_bf16 v[118:121], v[130:133], v[196:199], v[118:121]
	v_mfma_f32_16x16x32_bf16 v[114:117], v[138:141], v[196:199], v[114:117]
	v_mfma_f32_16x16x32_bf16 v[110:113], v[130:133], v[204:207], v[110:113]
	v_mfma_f32_16x16x32_bf16 v[106:109], v[138:141], v[204:207], v[106:109]
	v_mfma_f32_16x16x32_bf16 v[102:105], v[130:133], v[212:215], v[102:105]
	v_mfma_f32_16x16x32_bf16 v[98:101], v[138:141], v[212:215], v[98:101]
	v_mfma_f32_16x16x32_bf16 v[126:129], v[134:137], v[188:191], v[126:129]
	v_mfma_f32_16x16x32_bf16 v[122:125], v[142:145], v[188:191], v[122:125]
	v_mfma_f32_16x16x32_bf16 v[118:121], v[134:137], v[200:203], v[118:121]
	v_mfma_f32_16x16x32_bf16 v[114:117], v[142:145], v[200:203], v[114:117]
	v_mfma_f32_16x16x32_bf16 v[110:113], v[134:137], v[208:211], v[110:113]
	v_mfma_f32_16x16x32_bf16 v[106:109], v[142:145], v[208:211], v[106:109]
	v_mfma_f32_16x16x32_bf16 v[102:105], v[134:137], v[216:219], v[102:105]
	v_mfma_f32_16x16x32_bf16 v[98:101], v[142:145], v[216:219], v[98:101]
	s_setprio 0
	s_setprio 1
	v_mfma_f32_16x16x32_bf16 v[94:97], v[146:149], v[180:183], v[94:97]
	v_mfma_f32_16x16x32_bf16 v[90:93], v[166:169], v[180:183], v[90:93]
	v_mfma_f32_16x16x32_bf16 v[86:89], v[146:149], v[196:199], v[86:89]
	v_mfma_f32_16x16x32_bf16 v[82:85], v[166:169], v[196:199], v[82:85]
	v_mfma_f32_16x16x32_bf16 v[78:81], v[146:149], v[204:207], v[78:81]
	v_mfma_f32_16x16x32_bf16 v[74:77], v[166:169], v[204:207], v[74:77]
	v_mfma_f32_16x16x32_bf16 v[70:73], v[146:149], v[212:215], v[70:73]
	v_mfma_f32_16x16x32_bf16 v[66:69], v[166:169], v[212:215], v[66:69]
	v_mfma_f32_16x16x32_bf16 v[94:97], v[162:165], v[188:191], v[94:97]
	v_mfma_f32_16x16x32_bf16 v[90:93], v[170:173], v[188:191], v[90:93]
	v_mfma_f32_16x16x32_bf16 v[86:89], v[162:165], v[200:203], v[86:89]
	v_mfma_f32_16x16x32_bf16 v[82:85], v[170:173], v[200:203], v[82:85]
	v_mfma_f32_16x16x32_bf16 v[78:81], v[162:165], v[208:211], v[78:81]
	v_mfma_f32_16x16x32_bf16 v[74:77], v[170:173], v[208:211], v[74:77]
	v_mfma_f32_16x16x32_bf16 v[70:73], v[162:165], v[216:219], v[70:73]
	v_mfma_f32_16x16x32_bf16 v[66:69], v[170:173], v[216:219], v[66:69]
	s_setprio 0
	s_barrier
; #define PG8_STAGE(bufoff, gbase, voff) do { _Pragma("unroll") for (int _i = 0; _i < 2; ++_i) \
;         __builtin_amdgcn_global_load_lds((const unsigned*)((const char*)(gbase) + (voff)[_i]), (PG8_LAS unsigned*)(lds + (bufoff) + ldsw + _i * 8192), 16, 0, 0); } while (0)
; #define PG8_LDA(dst, b, h) do { _Pragma("unroll") for (int m = 0; m < 4; ++m) _Pragma("unroll") for (int k = 0; k < 2; ++k) dst[m][k] = *(const PG8_LAS bf16x8*)(lds + PG8_SA(b, h) + aoff + m * 2048 + k * 1024); } while (0)
; #define PG8_MMA(ai, bj, At, Bt) do { __builtin_amdgcn_s_setprio(1); _Pragma("unroll") for (int m = 0; m < 4; ++m) _Pragma("unroll") for (int n = 0; n < 2; ++n) _Pragma("unroll") for (int k = 0; k < 2; ++k) \
;         acc[ai][bj][m][n] = __builtin_amdgcn_mfma_f32_16x16x32_bf16(Bt[n][k], At[m][k], acc[ai][bj][m][n], 0, 0, 0); __builtin_amdgcn_s_setprio(0); } while (0)
; #define PG8_WAIT_V(n) asm volatile("s_waitcnt vmcnt(" #n ")" ::: "memory")
; #define PG8_WAIT_L(n) asm volatile("s_waitcnt lgkmcnt(" #n ")" ::: "memory")
; #define PG8_BAR __builtin_amdgcn_s_barrier()
; #define PG8_SCHED __builtin_amdgcn_sched_barrier(0)
; #define GAS __attribute__((address_space(1)))
; __device__ __forceinline__ size_t TX(int row, int col) { return ((((size_t)(row >> 8) * 16 + (col >> 6)) * 256 + (row & 255)) << 6) + (col & 63); }
; template <class Epi, class Sched, bool ALIGN_EPI = false, bool SP2 = false, bool ATILED = false, bool BTILED = false>
; __device__ __forceinline__ void gemm_phase(PG8_LAS unsigned char* lds, const Gemm g, const Sched& S, const Epi& E, const int tid) {
;     ...
;             PG8_WAIT_V(8); PG8_WAIT_L(0); PG8_BAR; PG8_MMA(0, 0, At, B0); PG8_MMA(0, 1, At, B1); PG8_BAR; PG8_SCHED;
;             PG8_LDA(At, 1, 1); PG8_STAGE(PG8_SB(1, 0), b3, voffB); PG8_STAGE(PG8_SB(1, 1), b3 + hstepB, voffB); PG8_STAGE(PG8_SA(1, 0), a3, voffA);
;             PG8_WAIT_V(8); PG8_WAIT_L(0); PG8_BAR; PG8_MMA(1, 0, At, B0); PG8_MMA(1, 1, At, B1); PG8_BAR; PG8_SCHED;
;     __device__ __forceinline__ void operator()(const f32x4 (&acc)[2][2][4][2], const pg8::Unit& u, int wr, int wc, int fr, int fq) const {
;     ...
;                 for (int m = 0; m < 4; ++m) xr[m] = *(const GAS u32x4*)(xres + TX(row0 + 128 * ai + 16 * m, col));
; #pragma unroll
;                 for (int n = 0; n < 2; ++n) ga4[n] = *(const GAS f32x4*)(ga + col + 4 * n);
	s_add_u32 s56, s54, 0x8000
	s_addc_u32 s57, s55, 0
	s_add_i32 s73, s73, s61
	v_lshl_add_u64 v[174:175], s[56:57], 0, v[152:153]
	s_mov_b32 m0, s73
	ds_read_b128 v[180:183], v186 offset:49152
	ds_read_b128 v[188:191], v186 offset:50176
	ds_read_b128 v[196:199], v186 offset:51200
	ds_read_b128 v[200:203], v186 offset:52224
	ds_read_b128 v[204:207], v186 offset:53248
	ds_read_b128 v[208:211], v186 offset:54272
	ds_read_b128 v[212:215], v186 offset:55296
	ds_read_b128 v[216:219], v186 offset:56320
	global_load_lds_dwordx4 v[174:175], off
	s_add_i32 m0, s73, 0x2000
	s_add_u32 s54, s54, 0xc000
	v_lshl_add_u64 v[174:175], s[56:57], 0, v[156:157]
	s_addc_u32 s55, s55, 0
	s_add_i32 s56, s74, s61
	global_load_lds_dwordx4 v[174:175], off
	v_lshl_add_u64 v[174:175], s[54:55], 0, v[152:153]
	s_mov_b32 m0, s56
	s_nop 0
	global_load_lds_dwordx4 v[174:175], off
	v_lshl_add_u64 v[174:175], s[54:55], 0, v[156:157]
	s_add_i32 m0, s56, 0x2000
	s_nop 0
	global_load_lds_dwordx4 v[174:175], off
	v_lshl_add_u64 v[174:175], s[52:53], 0, v[150:151]
	s_mov_b32 m0, s67
	s_nop 0
	global_load_lds_dwordx4 v[174:175], off
	v_lshl_add_u64 v[174:175], s[52:53], 0, v[154:155]
	s_mov_b32 m0, s68
	s_nop 0
	global_load_lds_dwordx4 v[174:175], off
	s_waitcnt vmcnt(8)
	s_cmp_lg_u32 s72, 12
	s_cbranch_scc1 .Lop_touch_skip
	s_lshl_b32 s98, s24, 4
	s_lshl_b32 s99, s26, 2
	s_add_i32 s98, s98, s99
	s_lshr_b32 s99, s66, 6
	s_add_i32 s98, s98, s99
	s_lshl_b32 s98, s98, 15
	s_lshl_b32 s99, s30, 7
	s_add_i32 s98, s98, s99
	s_and_b32 s99, s66, 63
	s_lshl_b32 s99, s99, 1
	s_add_i32 s98, s98, s99
	v_lshlrev_b32_e32 v253, 7, v1
	v_lshl_add_u32 v253, v176, 1, v253
	v_add_u32_e32 v253, s98, v253
	global_load_dword v231, v253, s[20:21]
	global_load_dword v231, v253, s[20:21] offset:2048
	v_add_u32_e32 v253, 0x1000, v253
	global_load_dword v231, v253, s[20:21]
	global_load_dword v231, v253, s[20:21] offset:2048
	v_add_u32_e32 v253, 0x3000, v253
	global_load_dword v231, v253, s[20:21]
	global_load_dword v231, v253, s[20:21] offset:2048
	v_add_u32_e32 v253, 0x1000, v253
	global_load_dword v231, v253, s[20:21]
	global_load_dword v231, v253, s[20:21] offset:2048
	v_add_u32_e32 v253, 0xb000, v253
	global_load_dword v231, v253, s[20:21]
	global_load_dword v231, v253, s[20:21] offset:2048
	v_add_u32_e32 v253, 0x1000, v253
	global_load_dword v231, v253, s[20:21]
	global_load_dword v231, v253, s[20:21] offset:2048
	v_add_u32_e32 v253, 0x3000, v253
	global_load_dword v231, v253, s[20:21]
	global_load_dword v231, v253, s[20:21] offset:2048
	v_add_u32_e32 v253, 0x1000, v253
	global_load_dword v231, v253, s[20:21]
	global_load_dword v231, v253, s[20:21] offset:2048
	s_lshl_b32 s98, s26, 10
	s_lshl_b32 s99, s66, 2
	s_add_i32 s98, s98, s99
	v_lshl_add_u32 v253, v176, 2, s98
	global_load_dword v231, v253, s[4:5]
	global_load_dword v231, v253, s[4:5] offset:512
.Lop_touch_skip:
	s_waitcnt lgkmcnt(0)
	s_barrier
	s_setprio 1
	s_waitcnt lgkmcnt(0)
	v_mfma_f32_16x16x32_bf16 v[62:65], v[130:133], v[180:183], v[62:65]
	v_mfma_f32_16x16x32_bf16 v[58:61], v[138:141], v[180:183], v[58:61]
	v_mfma_f32_16x16x32_bf16 v[54:57], v[130:133], v[196:199], v[54:57]
	v_mfma_f32_16x16x32_bf16 v[50:53], v[138:141], v[196:199], v[50:53]
	v_mfma_f32_16x16x32_bf16 v[46:49], v[130:133], v[204:207], v[46:49]
	v_mfma_f32_16x16x32_bf16 v[42:45], v[138:141], v[204:207], v[42:45]
	v_mfma_f32_16x16x32_bf16 v[38:41], v[130:133], v[212:215], v[38:41]
	v_mfma_f32_16x16x32_bf16 v[34:37], v[138:141], v[212:215], v[34:37]
	v_mfma_f32_16x16x32_bf16 v[62:65], v[134:137], v[188:191], v[62:65]
	v_mfma_f32_16x16x32_bf16 v[58:61], v[142:145], v[188:191], v[58:61]
	v_mfma_f32_16x16x32_bf16 v[54:57], v[134:137], v[200:203], v[54:57]
	v_mfma_f32_16x16x32_bf16 v[50:53], v[142:145], v[200:203], v[50:53]
	v_mfma_f32_16x16x32_bf16 v[46:49], v[134:137], v[208:211], v[46:49]
	v_mfma_f32_16x16x32_bf16 v[42:45], v[142:145], v[208:211], v[42:45]
	v_mfma_f32_16x16x32_bf16 v[38:41], v[134:137], v[216:219], v[38:41]
	v_mfma_f32_16x16x32_bf16 v[34:37], v[142:145], v[216:219], v[34:37]
	s_setprio 0
	s_setprio 1
	v_mfma_f32_16x16x32_bf16 v[30:33], v[146:149], v[180:183], v[30:33]
	v_mfma_f32_16x16x32_bf16 v[26:29], v[166:169], v[180:183], v[26:29]
	v_mfma_f32_16x16x32_bf16 v[22:25], v[146:149], v[196:199], v[22:25]
	v_mfma_f32_16x16x32_bf16 v[18:21], v[166:169], v[196:199], v[18:21]
	v_mfma_f32_16x16x32_bf16 v[14:17], v[146:149], v[204:207], v[14:17]
	v_mfma_f32_16x16x32_bf16 v[10:13], v[166:169], v[204:207], v[10:13]
	v_mfma_f32_16x16x32_bf16 v[6:9], v[146:149], v[212:215], v[6:9]
	v_mfma_f32_16x16x32_bf16 v[2:5], v[166:169], v[212:215], v[2:5]
	v_mfma_f32_16x16x32_bf16 v[30:33], v[162:165], v[188:191], v[30:33]
	v_mfma_f32_16x16x32_bf16 v[26:29], v[170:173], v[188:191], v[26:29]
	v_mfma_f32_16x16x32_bf16 v[22:25], v[162:165], v[200:203], v[22:25]
	v_mfma_f32_16x16x32_bf16 v[18:21], v[170:173], v[200:203], v[18:21]
	v_mfma_f32_16x16x32_bf16 v[14:17], v[162:165], v[208:211], v[14:17]
	v_mfma_f32_16x16x32_bf16 v[10:13], v[170:173], v[208:211], v[10:13]
	v_mfma_f32_16x16x32_bf16 v[6:9], v[162:165], v[216:219], v[6:9]
	v_mfma_f32_16x16x32_bf16 v[2:5], v[170:173], v[216:219], v[2:5]
	s_setprio 0
	s_barrier
	s_add_i32 s72, s72, 2
	s_add_u32 s28, s28, 0x10000
	s_addc_u32 s29, s29, 0
	s_add_u32 s25, s25, 0x10000
	s_addc_u32 s27, s27, 0
	s_cmp_gt_u32 s72, 13
	s_cbranch_scc0 .LBB0_233
; __device__ __forceinline__ unsigned cvt_pk_bf16(float lo, float hi) { unsigned r; asm volatile("v_cvt_pk_bf16_f32 %0, %1, %2" : "=v"(r) : "v"(lo), "v"(hi)); return r; }
; #define GAS __attribute__((address_space(1)))
; __device__ __forceinline__ size_t TX(int row, int col) { return ((((size_t)(row >> 8) * 16 + (col >> 6)) * 256 + (row & 255)) << 6) + (col & 63); }
; __device__ __forceinline__ float bf2f(unsigned b) { return __uint_as_float(b << 16); }
;     __device__ __forceinline__ void operator()(const f32x4 (&acc)[2][2][4][2], const pg8::Unit& u, int wr, int wc, int fr, int fq) const {
;         const int colb = 256 * u.pn + 32 * wc + 8 * fq, row0 = 256 * u.pm + 64 * wr + fr;
; #pragma unroll
;         for (int ai = 0; ai < 2; ++ai) {
;             float ss[4] = {0.f, 0.f, 0.f, 0.f};
; #pragma unroll
;             for (int bj = 0; bj < 2; ++bj) {
;                 const int col = colb + 128 * bj;
;                 u32x4 xr[4]; f32x4 ga4[2];
; #pragma unroll
;                 for (int m = 0; m < 4; ++m) xr[m] = *(const GAS u32x4*)(xres + TX(row0 + 128 * ai + 16 * m, col));
; #pragma unroll
;                 for (int n = 0; n < 2; ++n) ga4[n] = *(const GAS f32x4*)(ga + col + 4 * n);
; #pragma unroll
;                 for (int m = 0; m < 4; ++m) {
;                     const size_t off = (size_t)(row0 + 128 * ai + 16 * m) * DM + col;
;                     const f32x4 x0 = {bf2f(xr[m].x & 0xffffu), bf2f(xr[m].x >> 16), bf2f(xr[m].y & 0xffffu), bf2f(xr[m].y >> 16)};
;                     const f32x4 x1 = {bf2f(xr[m].z & 0xffffu), bf2f(xr[m].z >> 16), bf2f(xr[m].w & 0xffffu), bf2f(xr[m].w >> 16)};
;                     const f32x4 n0 = x0 + ga4[0] * acc[ai][bj][m][0], n1 = x1 + ga4[1] * acc[ai][bj][m][1];
;                     if (NXT) {
;                         u32x4 w; w.x = cvt_pk_bf16(n0[0], n0[1]); w.y = cvt_pk_bf16(n0[2], n0[3]); w.z = cvt_pk_bf16(n1[0], n1[1]); w.w = cvt_pk_bf16(n1[2], n1[3]);
;                         *(GAS u32x4*)(xres + TX(row0 + 128 * ai + 16 * m, col)) = w;
;                         { const f32x4 q = n0 * n0 + n1 * n1; ss[m] += (q[0] + q[1]) + (q[2] + q[3]); }
	s_lshl_b32 s11, s24, 8
	s_add_i32 s11, s11, s30
	s_lshl_b32 s9, s26, 8
	s_ashr_i32 s18, s11, 8
	s_or_b32 s9, s9, s66
	s_ashr_i32 s19, s18, 31
	s_lshl_b64 s[26:27], s[18:19], 12
	s_ashr_i32 s18, s9, 6
	s_ashr_i32 s19, s18, 31
	s_lshl_b64 s[24:25], s[18:19], 8
	v_or_b32_e32 v168, s9, v176
	v_bitop3_b32 v130, s9, 56, v176 bitop3:0xc8
	s_add_u32 s9, s26, s24
	v_or_b32_e32 v164, s11, v1
	v_bitop3_b32 v187, s11, v224, v1 bitop3:0xc8
	s_addc_u32 s11, s27, s25
	v_lshlrev_b32_e32 v178, 1, v130
	v_or_b32_e32 v130, s9, v187
	v_mov_b32_e32 v131, s11
	v_or_b32_e32 v190, 16, v187
	v_lshlrev_b64 v[192:193], 7, v[130:131]
	v_or_b32_e32 v130, s9, v190
	v_or_b32_e32 v188, 32, v187
	v_lshl_add_u64 v[162:163], s[20:21], 0, v[178:179]
	v_lshlrev_b64 v[174:175], 7, v[130:131]
	v_or_b32_e32 v130, s9, v188
	v_or_b32_e32 v189, 48, v187
	v_lshl_add_u64 v[132:133], v[162:163], 0, v[192:193]
	v_lshlrev_b64 v[172:173], 7, v[130:131]
	v_or_b32_e32 v130, s9, v189
	global_load_dwordx4 v[180:183], v[132:133], off
	v_subrev_u32_e32 v250, s20, v132
	v_lshl_add_u64 v[132:133], v[162:163], 0, v[174:175]
	v_lshlrev_b64 v[170:171], 7, v[130:131]
	v_ashrrev_i32_e32 v169, 31, v168
	global_load_dwordx4 v[146:149], v[132:133], off
	v_lshl_add_u64 v[132:133], v[162:163], 0, v[172:173]
	v_lshl_add_u64 v[130:131], v[162:163], 0, v[170:171]
	v_lshl_add_u64 v[166:167], v[168:169], 2, s[4:5]
	global_load_dwordx4 v[142:145], v[132:133], off
	v_lshl_add_u64 v[192:193], s[20:21], 0, v[192:193]
	global_load_dwordx4 v[130:133], v[130:131], off
	s_nop 0
	global_load_dwordx4 v[134:137], v[166:167], off offset:16
	global_load_dwordx4 v[138:141], v[166:167], off
	v_add_u32_e32 v252, 0x10000, v250
	global_load_dwordx4 v[200:203], v252, s[20:21]
	global_load_dwordx4 v[204:207], v252, s[20:21] offset:2048
	v_add_u32_e32 v252, 0x11000, v250
	global_load_dwordx4 v[208:211], v252, s[20:21]
	global_load_dwordx4 v[212:215], v252, s[20:21] offset:2048
	global_load_dwordx4 v[216:219], v[166:167], off offset:528
	global_load_dwordx4 v[150:153], v[166:167], off offset:512
	v_add_u32_e32 v252, 0x4000, v250
	global_load_dwordx4 v[154:157], v252, s[20:21]
	global_load_dwordx4 v[158:161], v252, s[20:21] offset:2048
	v_add_u32_e32 v252, 0x5000, v250
	global_load_dwordx4 v[228:231], v252, s[20:21]
	global_load_dwordx4 v[234:237], v252, s[20:21] offset:2048
	global_load_dwordx4 v[242:245], v[166:167], off offset:16
	global_load_dwordx4 v[246:249], v[166:167], off
	v_lshl_add_u64 v[192:193], v[192:193], 0, v[178:179]
	v_ashrrev_i32_e32 v165, 31, v164
	s_waitcnt vmcnt(12)
	v_lshlrev_b32_e32 v196, 16, v180
	v_and_b32_e32 v197, 0xffff0000, v180
	v_lshlrev_b32_e32 v180, 16, v181
	v_and_b32_e32 v181, 0xffff0000, v181
	v_lshlrev_b32_e32 v198, 16, v182
	v_and_b32_e32 v199, 0xffff0000, v182
	v_lshlrev_b32_e32 v182, 16, v183
	v_and_b32_e32 v183, 0xffff0000, v183
	v_pk_fma_f32 v[128:129], v[128:129], v[140:141], v[180:181]
	v_pk_fma_f32 v[126:127], v[126:127], v[138:139], v[196:197]
	v_pk_fma_f32 v[180:181], v[124:125], v[136:137], v[182:183]
	v_pk_fma_f32 v[182:183], v[122:123], v[134:135], v[198:199]
	v_cvt_pk_bf16_f32 v122, v126, v127
	v_cvt_pk_bf16_f32 v123, v128, v129
	s_nop 0
	v_cvt_pk_bf16_f32 v124, v182, v183
	v_cvt_pk_bf16_f32 v125, v180, v181
	global_store_dwordx4 v[192:193], v[122:125], off
	s_nop 1
	v_pk_mul_f32 v[122:123], v[182:183], v[182:183]
	v_pk_mul_f32 v[124:125], v[180:181], v[180:181]
	v_pk_fma_f32 v[122:123], v[126:127], v[126:127], v[122:123]
	v_pk_fma_f32 v[124:125], v[128:129], v[128:129], v[124:125]
	v_add_f32_e32 v122, v122, v123
	v_add_f32_e32 v123, v124, v125
	v_lshlrev_b32_e32 v124, 16, v146
	v_and_b32_e32 v125, 0xffff0000, v146
	v_add_f32_e32 v191, v122, v123
	v_lshlrev_b32_e32 v122, 16, v147
	v_and_b32_e32 v123, 0xffff0000, v147
	v_lshlrev_b32_e32 v128, 16, v148
	v_and_b32_e32 v129, 0xffff0000, v148
	v_pk_fma_f32 v[124:125], v[118:119], v[138:139], v[124:125]
	v_lshl_add_u64 v[118:119], s[20:21], 0, v[174:175]
	v_lshlrev_b32_e32 v126, 16, v149
	v_and_b32_e32 v127, 0xffff0000, v149
	v_pk_fma_f32 v[122:123], v[120:121], v[140:141], v[122:123]
	v_pk_fma_f32 v[128:129], v[114:115], v[134:135], v[128:129]
	v_cvt_pk_bf16_f32 v114, v124, v125
	v_cvt_pk_bf16_f32 v115, v122, v123
	v_lshl_add_u64 v[118:119], v[118:119], 0, v[178:179]
	v_pk_fma_f32 v[126:127], v[116:117], v[136:137], v[126:127]
	v_cvt_pk_bf16_f32 v116, v128, v129
	v_lshlrev_b32_e32 v120, 16, v145
	v_cvt_pk_bf16_f32 v117, v126, v127
	global_store_dwordx4 v[118:119], v[114:117], off
	v_lshlrev_b32_e32 v118, 16, v144
	v_and_b32_e32 v119, 0xffff0000, v144
	v_lshlrev_b32_e32 v114, 16, v142
	v_and_b32_e32 v115, 0xffff0000, v142
	v_lshlrev_b32_e32 v116, 16, v143
	v_and_b32_e32 v117, 0xffff0000, v143
	v_and_b32_e32 v121, 0xffff0000, v145
	v_pk_fma_f32 v[144:145], v[110:111], v[138:139], v[114:115]
	v_lshl_add_u64 v[110:111], s[20:21], 0, v[172:173]
	v_pk_fma_f32 v[142:143], v[112:113], v[140:141], v[116:117]
	v_pk_fma_f32 v[148:149], v[106:107], v[134:135], v[118:119]
	v_cvt_pk_bf16_f32 v106, v144, v145
	v_cvt_pk_bf16_f32 v107, v142, v143
	v_lshl_add_u64 v[110:111], v[110:111], 0, v[178:179]
	v_pk_fma_f32 v[146:147], v[108:109], v[136:137], v[120:121]
	v_cvt_pk_bf16_f32 v108, v148, v149
	v_lshlrev_b32_e32 v112, 16, v133
	v_cvt_pk_bf16_f32 v109, v146, v147
	global_store_dwordx4 v[110:111], v[106:109], off
	v_lshlrev_b32_e32 v110, 16, v132
	v_and_b32_e32 v111, 0xffff0000, v132
	v_lshlrev_b32_e32 v106, 16, v130
	v_and_b32_e32 v107, 0xffff0000, v130
	v_and_b32_e32 v113, 0xffff0000, v133
	v_pk_fma_f32 v[132:133], v[102:103], v[138:139], v[106:107]
	v_lshl_add_u64 v[102:103], s[20:21], 0, v[170:171]
	v_lshlrev_b32_e32 v108, 16, v131
; __device__ __forceinline__ unsigned cvt_pk_bf16(float lo, float hi) { unsigned r; asm volatile("v_cvt_pk_bf16_f32 %0, %1, %2" : "=v"(r) : "v"(lo), "v"(hi)); return r; }
; #define GAS __attribute__((address_space(1)))
; __device__ __forceinline__ size_t TX(int row, int col) { return ((((size_t)(row >> 8) * 16 + (col >> 6)) * 256 + (row & 255)) << 6) + (col & 63); }
; __device__ __forceinline__ float bf2f(unsigned b) { return __uint_as_float(b << 16); }
;     __device__ __forceinline__ void operator()(const f32x4 (&acc)[2][2][4][2], const pg8::Unit& u, int wr, int wc, int fr, int fq) const {
;     ...
;                 for (int m = 0; m < 4; ++m) xr[m] = *(const GAS u32x4*)(xres + TX(row0 + 128 * ai + 16 * m, col));
; #pragma unroll
;                 for (int n = 0; n < 2; ++n) ga4[n] = *(const GAS f32x4*)(ga + col + 4 * n);
; #pragma unroll
;                 for (int m = 0; m < 4; ++m) {
;                     const size_t off = (size_t)(row0 + 128 * ai + 16 * m) * DM + col;
;                     const f32x4 x0 = {bf2f(xr[m].x & 0xffffu), bf2f(xr[m].x >> 16), bf2f(xr[m].y & 0xffffu), bf2f(xr[m].y >> 16)};
;                     const f32x4 x1 = {bf2f(xr[m].z & 0xffffu), bf2f(xr[m].z >> 16), bf2f(xr[m].w & 0xffffu), bf2f(xr[m].w >> 16)};
;                     const f32x4 n0 = x0 + ga4[0] * acc[ai][bj][m][0], n1 = x1 + ga4[1] * acc[ai][bj][m][1];
;                     if (NXT) {
;                         u32x4 w; w.x = cvt_pk_bf16(n0[0], n0[1]); w.y = cvt_pk_bf16(n0[2], n0[3]); w.z = cvt_pk_bf16(n1[0], n1[1]); w.w = cvt_pk_bf16(n1[2], n1[3]);
;                         *(GAS u32x4*)(xres + TX(row0 + 128 * ai + 16 * m, col)) = w;
;                         { const f32x4 q = n0 * n0 + n1 * n1; ss[m] += (q[0] + q[1]) + (q[2] + q[3]); }
;                     } else { *(GAS f32x4*)(fout + off) = n0; *(GAS f32x4*)(fout + off + 4) = n1; }
;                 }
;             }
;             if (NXT) {
; #pragma unroll
;                 for (int m = 0; m < 4; ++m) { float s = ss[m]; s += __shfl_xor(s, 16); s += __shfl_xor(s, 32);
;                     if (fq == 0) __hip_atomic_fetch_add(ssq_out + row0 + 128 * ai + 16 * m, (unsigned)(s * 1024.0f + 0.5f), __ATOMIC_RELAXED, __HIP_MEMORY_SCOPE_AGENT); }
	v_and_b32_e32 v109, 0xffff0000, v131
	v_lshl_add_u64 v[102:103], v[102:103], 0, v[178:179]
	v_pk_fma_f32 v[130:131], v[104:105], v[140:141], v[108:109]
	v_pk_fma_f32 v[136:137], v[100:101], v[136:137], v[112:113]
	v_pk_fma_f32 v[134:135], v[98:99], v[134:135], v[110:111]
	v_cvt_pk_bf16_f32 v98, v132, v133
	v_cvt_pk_bf16_f32 v99, v130, v131
	s_nop 0
	v_cvt_pk_bf16_f32 v100, v134, v135
	v_cvt_pk_bf16_f32 v101, v136, v137
	global_store_dwordx4 v[102:103], v[98:101], off
	v_or_b32_e32 v102, 0x80, v168
	v_ashrrev_i32_e32 v103, 31, v102
	v_ashrrev_i32_e32 v98, 6, v102
	v_ashrrev_i32_e32 v99, 31, v98
	v_lshlrev_b64 v[120:121], 8, v[98:99]
	v_lshl_add_u64 v[98:99], v[120:121], 0, s[26:27]
	v_or_b32_e32 v100, v98, v187
	v_mov_b32_e32 v101, v99
	v_lshlrev_b64 v[174:175], 7, v[100:101]
	v_lshl_add_u64 v[100:101], v[162:163], 0, v[174:175]
	v_or_b32_e32 v100, v98, v190
	v_mov_b32_e32 v101, v99
	v_lshlrev_b64 v[168:169], 7, v[100:101]
	v_lshl_add_u64 v[100:101], v[162:163], 0, v[168:169]
	v_or_b32_e32 v100, v98, v188
	v_mov_b32_e32 v101, v99
	v_or_b32_e32 v98, v98, v189
	v_lshlrev_b64 v[140:141], 7, v[100:101]
	v_lshlrev_b64 v[138:139], 7, v[98:99]
	v_lshl_add_u64 v[100:101], v[162:163], 0, v[140:141]
	v_lshl_add_u64 v[98:99], v[162:163], 0, v[138:139]
	v_lshl_add_u64 v[118:119], v[102:103], 2, s[4:5]
	v_lshl_add_u64 v[174:175], s[20:21], 0, v[174:175]
	s_nop 0
	v_lshl_add_u64 v[174:175], v[174:175], 0, v[178:179]
	s_waitcnt vmcnt(10)
	v_mov_b32_e32 v170, v200
	v_mov_b32_e32 v171, v201
	v_mov_b32_e32 v172, v202
	v_mov_b32_e32 v173, v203
	v_mov_b32_e32 v114, v204
	v_mov_b32_e32 v115, v205
	v_mov_b32_e32 v116, v206
	v_mov_b32_e32 v117, v207
	v_mov_b32_e32 v106, v208
	v_mov_b32_e32 v107, v209
	v_mov_b32_e32 v108, v210
	v_mov_b32_e32 v109, v211
	v_mov_b32_e32 v98, v212
	v_mov_b32_e32 v99, v213
	v_mov_b32_e32 v100, v214
	v_mov_b32_e32 v101, v215
	v_mov_b32_e32 v102, v216
	v_mov_b32_e32 v103, v217
	v_mov_b32_e32 v104, v218
	v_mov_b32_e32 v105, v219
	v_mov_b32_e32 v110, v150
	v_mov_b32_e32 v111, v151
	v_mov_b32_e32 v112, v152
	v_mov_b32_e32 v113, v153
	v_add_u32_e32 v252, 0x14000, v250
	global_load_dwordx4 v[200:203], v252, s[20:21]
	global_load_dwordx4 v[204:207], v252, s[20:21] offset:2048
	v_add_u32_e32 v252, 0x15000, v250
	global_load_dwordx4 v[208:211], v252, s[20:21]
	global_load_dwordx4 v[212:215], v252, s[20:21] offset:2048
	global_load_dwordx4 v[216:219], v[166:167], off offset:528
	global_load_dwordx4 v[150:153], v[166:167], off offset:512
	v_lshlrev_b32_e32 v180, 16, v170
	v_and_b32_e32 v181, 0xffff0000, v170
	v_lshlrev_b32_e32 v170, 16, v171
	v_and_b32_e32 v171, 0xffff0000, v171
	v_lshlrev_b32_e32 v182, 16, v172
	v_and_b32_e32 v183, 0xffff0000, v172
	v_lshlrev_b32_e32 v172, 16, v173
	v_and_b32_e32 v173, 0xffff0000, v173
	v_pk_fma_f32 v[96:97], v[96:97], v[112:113], v[170:171]
	v_pk_fma_f32 v[94:95], v[94:95], v[110:111], v[180:181]
	v_pk_fma_f32 v[170:171], v[92:93], v[104:105], v[172:173]
	v_pk_fma_f32 v[172:173], v[90:91], v[102:103], v[182:183]
	v_cvt_pk_bf16_f32 v90, v94, v95
	v_cvt_pk_bf16_f32 v91, v96, v97
	s_nop 0
	v_cvt_pk_bf16_f32 v92, v172, v173
	v_cvt_pk_bf16_f32 v93, v170, v171
	global_store_dwordx4 v[174:175], v[90:93], off
	s_nop 1
	v_pk_mul_f32 v[90:91], v[172:173], v[172:173]
	v_pk_mul_f32 v[92:93], v[170:171], v[170:171]
	v_pk_fma_f32 v[90:91], v[94:95], v[94:95], v[90:91]
	v_pk_fma_f32 v[92:93], v[96:97], v[96:97], v[92:93]
	v_add_f32_e32 v90, v90, v91
	v_add_f32_e32 v91, v92, v93
	v_add_f32_e32 v90, v90, v91
	v_add_f32_e32 v170, v191, v90
	v_lshlrev_b32_e32 v90, 16, v114
	v_and_b32_e32 v91, 0xffff0000, v114
	v_lshlrev_b32_e32 v94, 16, v116
	v_and_b32_e32 v95, 0xffff0000, v116
	v_pk_fma_f32 v[86:87], v[86:87], v[110:111], v[90:91]
	v_pk_fma_f32 v[90:91], v[82:83], v[102:103], v[94:95]
	v_lshl_add_u64 v[82:83], s[20:21], 0, v[168:169]
	v_lshlrev_b32_e32 v92, 16, v115
	v_and_b32_e32 v93, 0xffff0000, v115
	v_lshlrev_b32_e32 v96, 16, v117
	v_and_b32_e32 v97, 0xffff0000, v117
	v_lshl_add_u64 v[82:83], v[82:83], 0, v[178:179]
	v_pk_fma_f32 v[88:89], v[88:89], v[112:113], v[92:93]
	v_pk_fma_f32 v[84:85], v[84:85], v[104:105], v[96:97]
	v_cvt_pk_bf16_f32 v92, v86, v87
	v_cvt_pk_bf16_f32 v93, v88, v89
	v_cvt_pk_bf16_f32 v94, v90, v91
	v_lshlrev_b32_e32 v96, 16, v109
	v_cvt_pk_bf16_f32 v95, v84, v85
	global_store_dwordx4 v[82:83], v[92:95], off
	v_lshlrev_b32_e32 v82, 16, v106
	v_and_b32_e32 v83, 0xffff0000, v106
	v_pk_fma_f32 v[78:79], v[78:79], v[110:111], v[82:83]
	v_lshl_add_u64 v[82:83], s[20:21], 0, v[140:141]
	v_lshlrev_b32_e32 v92, 16, v107
	v_and_b32_e32 v93, 0xffff0000, v107
	v_lshlrev_b32_e32 v94, 16, v108
	v_and_b32_e32 v95, 0xffff0000, v108
	v_and_b32_e32 v97, 0xffff0000, v109
	v_lshl_add_u64 v[82:83], v[82:83], 0, v[178:179]
	v_pk_fma_f32 v[80:81], v[80:81], v[112:113], v[92:93]
	v_pk_fma_f32 v[76:77], v[76:77], v[104:105], v[96:97]
	v_pk_fma_f32 v[74:75], v[74:75], v[102:103], v[94:95]
	v_cvt_pk_bf16_f32 v92, v78, v79
	v_cvt_pk_bf16_f32 v93, v80, v81
	v_lshlrev_b32_e32 v96, 16, v101
	v_cvt_pk_bf16_f32 v94, v74, v75
	v_cvt_pk_bf16_f32 v95, v76, v77
	global_store_dwordx4 v[82:83], v[92:95], off
	v_lshlrev_b32_e32 v82, 16, v98
	v_and_b32_e32 v83, 0xffff0000, v98
	v_pk_fma_f32 v[70:71], v[70:71], v[110:111], v[82:83]
	v_lshl_add_u64 v[82:83], s[20:21], 0, v[138:139]
	v_lshlrev_b32_e32 v92, 16, v99
	v_and_b32_e32 v93, 0xffff0000, v99
	v_lshlrev_b32_e32 v94, 16, v100
	v_and_b32_e32 v95, 0xffff0000, v100
	v_and_b32_e32 v97, 0xffff0000, v101
	v_lshl_add_u64 v[82:83], v[82:83], 0, v[178:179]
	v_pk_fma_f32 v[72:73], v[72:73], v[112:113], v[92:93]
	v_pk_fma_f32 v[68:69], v[68:69], v[104:105], v[96:97]
	v_pk_fma_f32 v[66:67], v[66:67], v[102:103], v[94:95]
	v_cvt_pk_bf16_f32 v92, v70, v71
	v_cvt_pk_bf16_f32 v93, v72, v73
	s_nop 0
	v_cvt_pk_bf16_f32 v94, v66, v67
	v_cvt_pk_bf16_f32 v95, v68, v69
	global_store_dwordx4 v[82:83], v[92:95], off
	v_and_b32_e32 v83, 64, v232
	v_xor_b32_e32 v82, 16, v232
	v_add_u32_e32 v83, 64, v83
	v_cmp_lt_i32_e32 vcc, v82, v83
	s_nop 1
	v_cndmask_b32_e32 v82, v232, v82, vcc
	v_lshlrev_b32_e32 v92, 2, v82
	v_xor_b32_e32 v82, 32, v232
	v_cmp_lt_i32_e32 vcc, v82, v83
	s_nop 1
	v_cndmask_b32_e32 v82, v232, v82, vcc
	v_lshlrev_b32_e32 v93, 2, v82
	ds_bpermute_b32 v82, v92, v170
	s_waitcnt lgkmcnt(0)
	v_add_f32_e32 v94, v170, v82
	ds_bpermute_b32 v95, v93, v94
	v_lshl_add_u64 v[82:83], v[164:165], 2, s[6:7]
	s_and_saveexec_b64 s[26:27], s[0:1]
	s_mov_b32 s9, 0x44800000
	s_cbranch_execz .LBB0_236
	s_waitcnt lgkmcnt(0)
	v_add_f32_e32 v94, v94, v95
	v_fma_f32 v94, v94, s9, 0.5
	v_cvt_u32_f32_e32 v94, v94
	global_atomic_add v[82:83], v94, off

; #define PG8_STAGE(bufoff, gbase, voff) do { _Pragma("unroll") for (int _i = 0; _i < 2; ++_i) \
;         __builtin_amdgcn_global_load_lds((const unsigned*)((const char*)(gbase) + (voff)[_i]), (PG8_LAS unsigned*)(lds + (bufoff) + ldsw + _i * 8192), 16, 0, 0); } while (0)
; #define PG8_LDA(dst, b, h) do { _Pragma("unroll") for (int m = 0; m < 4; ++m) _Pragma("unroll") for (int k = 0; k < 2; ++k) dst[m][k] = *(const PG8_LAS bf16x8*)(lds + PG8_SA(b, h) + aoff + m * 2048 + k * 1024); } while (0)
; #define PG8_LDB(dst, b, h) do { _Pragma("unroll") for (int n = 0; n < 2; ++n) _Pragma("unroll") for (int k = 0; k < 2; ++k) dst[n][k] = *(const PG8_LAS bf16x8*)(lds + PG8_SB(b, h) + boff + n * 2048 + k * 1024); } while (0)
; #define PG8_MMA(ai, bj, At, Bt) do { __builtin_amdgcn_s_setprio(1); _Pragma("unroll") for (int m = 0; m < 4; ++m) _Pragma("unroll") for (int n = 0; n < 2; ++n) _Pragma("unroll") for (int k = 0; k < 2; ++k) \
;         acc[ai][bj][m][n] = __builtin_amdgcn_mfma_f32_16x16x32_bf16(Bt[n][k], At[m][k], acc[ai][bj][m][n], 0, 0, 0); __builtin_amdgcn_s_setprio(0); } while (0)
; #define PG8_WAIT_V(n) asm volatile("s_waitcnt vmcnt(" #n ")" ::: "memory")
; #define PG8_WAIT_L(n) asm volatile("s_waitcnt lgkmcnt(" #n ")" ::: "memory")
; #define PG8_BAR __builtin_amdgcn_s_barrier()
; template <class Epi, class Sched, bool ALIGN_EPI = false, bool SP2 = false, bool ATILED = false, bool BTILED = false>
; __device__ __forceinline__ void gemm_phase(PG8_LAS unsigned char* lds, const Gemm g, const Sched& S, const Epi& E, const int tid) {
;     ...
;             const bool last = (t == nt - 2);
;             const char* a1 = cA + (size_t)(t + 1) * kstepA;
;             const char* a2 = last ? nA : cA + (size_t)(t + 2) * kstepA; const char* b2 = last ? nB : cB + (size_t)(t + 2) * kstepB;
;             const char* a3 = a2 + kstepA; const char* b3 = b2 + kstepB;
;             if (last && has_next) S.a_ready(nxt);
;             if constexpr (SP2) {
;             PG8_LDB(B0, 0, 0); PG8_LDB(B1, 0, 1); PG8_SCHED; PG8_LDA(At, 0, 0); PG8_STAGE(PG8_SA(1, 1), a1 + hstepA, voffA);
;             PG8_WAIT_V(8); PG8_WAIT_L(0); PG8_BAR; PG8_MMA(0, 0, At, B0); PG8_MMA(0, 1, At, B1); PG8_BAR; PG8_SCHED;
;             PG8_LDA(At, 0, 1); PG8_STAGE(PG8_SB(0, 0), b2, voffB); PG8_STAGE(PG8_SB(0, 1), b2 + hstepB, voffB); PG8_STAGE(PG8_SA(0, 0), a2, voffA);
.LBB0_478:
	s_add_u32 s18, s16, 0x4000
	s_addc_u32 s19, s17, 0
	s_cmp_eq_u32 s69, 40
	s_cselect_b32 s26, s4, s18
	s_cselect_b32 s27, s5, s19
	s_cselect_b32 s24, s14, s67
	s_cselect_b32 s25, s15, s68
	s_add_u32 s18, s26, 0x8000
	s_addc_u32 s19, s27, 0
	s_add_i32 s70, 0, 0x10000
	s_add_i32 s72, 0, 0x14000
	v_add_u32_e32 v142, s70, v177
	v_add_u32_e32 v170, s72, v177
	ds_read_b128 v[130:133], v142
	ds_read_b128 v[134:137], v142 offset:1024
	ds_read_b128 v[138:141], v142 offset:2048
	ds_read_b128 v[142:145], v142 offset:3072
	ds_read_b128 v[146:149], v170
	ds_read_b128 v[162:165], v170 offset:1024
	ds_read_b128 v[166:169], v170 offset:2048
	ds_read_b128 v[170:173], v170 offset:3072
	v_lshl_add_u64 v[174:175], s[16:17], 0, v[158:159]
	s_add_i32 m0, s53, 0xc000
	ds_read_b128 v[180:183], v184
	ds_read_b128 v[186:189], v184 offset:1024
	ds_read_b128 v[190:193], v184 offset:2048
	ds_read_b128 v[196:199], v184 offset:3072
	ds_read_b128 v[200:203], v184 offset:4096
	ds_read_b128 v[204:207], v184 offset:5120
	ds_read_b128 v[208:211], v184 offset:6144
	ds_read_b128 v[212:215], v184 offset:7168
	global_load_lds_dwordx4 v[174:175], off
	v_lshl_add_u64 v[174:175], s[16:17], 0, v[160:161]
	s_add_i32 m0, s53, 0xe000
	s_nop 0
	global_load_lds_dwordx4 v[174:175], off
	s_waitcnt vmcnt(8)
	s_waitcnt lgkmcnt(0)
	s_barrier
	s_setprio 1
	s_waitcnt lgkmcnt(0)
	v_mfma_f32_16x16x32_bf16 v[126:129], v[130:133], v[180:183], v[126:129]
	v_mfma_f32_16x16x32_bf16 v[122:125], v[138:141], v[180:183], v[122:125]
	v_mfma_f32_16x16x32_bf16 v[118:121], v[130:133], v[190:193], v[118:121]
	v_mfma_f32_16x16x32_bf16 v[114:117], v[138:141], v[190:193], v[114:117]
	v_mfma_f32_16x16x32_bf16 v[110:113], v[130:133], v[200:203], v[110:113]
	v_mfma_f32_16x16x32_bf16 v[106:109], v[138:141], v[200:203], v[106:109]
	v_mfma_f32_16x16x32_bf16 v[102:105], v[130:133], v[208:211], v[102:105]
	v_mfma_f32_16x16x32_bf16 v[98:101], v[138:141], v[208:211], v[98:101]
	v_mfma_f32_16x16x32_bf16 v[126:129], v[134:137], v[186:189], v[126:129]
	v_mfma_f32_16x16x32_bf16 v[122:125], v[142:145], v[186:189], v[122:125]
	v_mfma_f32_16x16x32_bf16 v[118:121], v[134:137], v[196:199], v[118:121]
	v_mfma_f32_16x16x32_bf16 v[114:117], v[142:145], v[196:199], v[114:117]
	v_mfma_f32_16x16x32_bf16 v[110:113], v[134:137], v[204:207], v[110:113]
	v_mfma_f32_16x16x32_bf16 v[106:109], v[142:145], v[204:207], v[106:109]
	v_mfma_f32_16x16x32_bf16 v[102:105], v[134:137], v[212:215], v[102:105]
	v_mfma_f32_16x16x32_bf16 v[98:101], v[142:145], v[212:215], v[98:101]
	s_setprio 0
	s_setprio 1
	v_mfma_f32_16x16x32_bf16 v[94:97], v[146:149], v[180:183], v[94:97]
	v_mfma_f32_16x16x32_bf16 v[90:93], v[166:169], v[180:183], v[90:93]
	v_mfma_f32_16x16x32_bf16 v[86:89], v[146:149], v[190:193], v[86:89]
	v_mfma_f32_16x16x32_bf16 v[82:85], v[166:169], v[190:193], v[82:85]
	v_mfma_f32_16x16x32_bf16 v[78:81], v[146:149], v[200:203], v[78:81]
	v_mfma_f32_16x16x32_bf16 v[74:77], v[166:169], v[200:203], v[74:77]
	v_mfma_f32_16x16x32_bf16 v[70:73], v[146:149], v[208:211], v[70:73]
	v_mfma_f32_16x16x32_bf16 v[66:69], v[166:169], v[208:211], v[66:69]
	v_mfma_f32_16x16x32_bf16 v[94:97], v[162:165], v[186:189], v[94:97]
	v_mfma_f32_16x16x32_bf16 v[90:93], v[170:173], v[186:189], v[90:93]
	v_mfma_f32_16x16x32_bf16 v[86:89], v[162:165], v[196:199], v[86:89]
	v_mfma_f32_16x16x32_bf16 v[82:85], v[170:173], v[196:199], v[82:85]
	v_mfma_f32_16x16x32_bf16 v[78:81], v[162:165], v[204:207], v[78:81]
	v_mfma_f32_16x16x32_bf16 v[74:77], v[170:173], v[204:207], v[74:77]
	v_mfma_f32_16x16x32_bf16 v[70:73], v[162:165], v[212:215], v[70:73]
	v_mfma_f32_16x16x32_bf16 v[66:69], v[170:173], v[212:215], v[66:69]
	s_setprio 0
	s_barrier
	s_add_i32 s70, s70, s52
	v_lshl_add_u64 v[174:175], s[24:25], 0, v[152:153]
	s_mov_b32 m0, s70
	ds_read_b128 v[180:183], v184 offset:16384
	ds_read_b128 v[186:189], v184 offset:17408
	ds_read_b128 v[190:193], v184 offset:18432
	ds_read_b128 v[196:199], v184 offset:19456
	ds_read_b128 v[200:203], v184 offset:20480
	ds_read_b128 v[204:207], v184 offset:21504
	ds_read_b128 v[208:211], v184 offset:22528
	ds_read_b128 v[212:215], v184 offset:23552
	global_load_lds_dwordx4 v[174:175], off
	s_add_i32 m0, s70, 0x2000
	s_add_u32 s70, s24, 0x4000
	v_lshl_add_u64 v[174:175], s[24:25], 0, v[156:157]
	s_addc_u32 s71, s25, 0
	s_add_i32 s72, s72, s52
	global_load_lds_dwordx4 v[174:175], off
	v_lshl_add_u64 v[174:175], s[70:71], 0, v[152:153]
	s_mov_b32 m0, s72
	s_nop 0
	global_load_lds_dwordx4 v[174:175], off
	v_lshl_add_u64 v[174:175], s[70:71], 0, v[156:157]
	s_add_i32 m0, s72, 0x2000
	s_nop 0
	global_load_lds_dwordx4 v[174:175], off
	v_lshl_add_u64 v[174:175], s[26:27], 0, v[150:151]
	s_mov_b32 m0, s53
	s_nop 0
	global_load_lds_dwordx4 v[174:175], off
	v_lshl_add_u64 v[174:175], s[26:27], 0, v[154:155]
	s_mov_b32 m0, s54
	s_nop 0
	global_load_lds_dwordx4 v[174:175], off
	s_waitcnt vmcnt(8)
	s_waitcnt lgkmcnt(0)
	s_barrier
; #define PG8_STAGE(bufoff, gbase, voff) do { _Pragma("unroll") for (int _i = 0; _i < 2; ++_i) \
;         __builtin_amdgcn_global_load_lds((const unsigned*)((const char*)(gbase) + (voff)[_i]), (PG8_LAS unsigned*)(lds + (bufoff) + ldsw + _i * 8192), 16, 0, 0); } while (0)
; #define PG8_LDA(dst, b, h) do { _Pragma("unroll") for (int m = 0; m < 4; ++m) _Pragma("unroll") for (int k = 0; k < 2; ++k) dst[m][k] = *(const PG8_LAS bf16x8*)(lds + PG8_SA(b, h) + aoff + m * 2048 + k * 1024); } while (0)
; #define PG8_LDB(dst, b, h) do { _Pragma("unroll") for (int n = 0; n < 2; ++n) _Pragma("unroll") for (int k = 0; k < 2; ++k) dst[n][k] = *(const PG8_LAS bf16x8*)(lds + PG8_SB(b, h) + boff + n * 2048 + k * 1024); } while (0)
; #define PG8_MMA(ai, bj, At, Bt) do { __builtin_amdgcn_s_setprio(1); _Pragma("unroll") for (int m = 0; m < 4; ++m) _Pragma("unroll") for (int n = 0; n < 2; ++n) _Pragma("unroll") for (int k = 0; k < 2; ++k) \
;         acc[ai][bj][m][n] = __builtin_amdgcn_mfma_f32_16x16x32_bf16(Bt[n][k], At[m][k], acc[ai][bj][m][n], 0, 0, 0); __builtin_amdgcn_s_setprio(0); } while (0)
; #define PG8_WAIT_V(n) asm volatile("s_waitcnt vmcnt(" #n ")" ::: "memory")
; #define PG8_WAIT_L(n) asm volatile("s_waitcnt lgkmcnt(" #n ")" ::: "memory")
; #define PG8_BAR __builtin_amdgcn_s_barrier()
; #define PG8_SCHED __builtin_amdgcn_sched_barrier(0)
; template <class Epi, class Sched, bool ALIGN_EPI = false, bool SP2 = false, bool ATILED = false, bool BTILED = false>
; __device__ __forceinline__ void gemm_phase(PG8_LAS unsigned char* lds, const Gemm g, const Sched& S, const Epi& E, const int tid) {
;     ...
;             PG8_WAIT_V(8); PG8_WAIT_L(0); PG8_BAR; PG8_MMA(1, 0, At, B0); PG8_MMA(1, 1, At, B1); PG8_BAR; PG8_SCHED;
;             PG8_LDB(B0, 1, 0); PG8_LDB(B1, 1, 1); PG8_SCHED; PG8_LDA(At, 1, 0); PG8_STAGE(PG8_SA(0, 1), a2 + hstepA, voffA);
;             PG8_WAIT_V(8); PG8_WAIT_L(0); PG8_BAR; PG8_MMA(0, 0, At, B0); PG8_MMA(0, 1, At, B1); PG8_BAR; PG8_SCHED;
	s_setprio 1
	s_waitcnt lgkmcnt(0)
	v_mfma_f32_16x16x32_bf16 v[62:65], v[130:133], v[180:183], v[62:65]
	v_mfma_f32_16x16x32_bf16 v[58:61], v[138:141], v[180:183], v[58:61]
	v_mfma_f32_16x16x32_bf16 v[54:57], v[130:133], v[190:193], v[54:57]
	v_mfma_f32_16x16x32_bf16 v[50:53], v[138:141], v[190:193], v[50:53]
	v_mfma_f32_16x16x32_bf16 v[46:49], v[130:133], v[200:203], v[46:49]
	v_mfma_f32_16x16x32_bf16 v[42:45], v[138:141], v[200:203], v[42:45]
	v_mfma_f32_16x16x32_bf16 v[38:41], v[130:133], v[208:211], v[38:41]
	v_mfma_f32_16x16x32_bf16 v[34:37], v[138:141], v[208:211], v[34:37]
	v_mfma_f32_16x16x32_bf16 v[62:65], v[134:137], v[186:189], v[62:65]
	v_mfma_f32_16x16x32_bf16 v[58:61], v[142:145], v[186:189], v[58:61]
	v_mfma_f32_16x16x32_bf16 v[54:57], v[134:137], v[196:199], v[54:57]
	v_mfma_f32_16x16x32_bf16 v[50:53], v[142:145], v[196:199], v[50:53]
	v_mfma_f32_16x16x32_bf16 v[46:49], v[134:137], v[204:207], v[46:49]
	v_mfma_f32_16x16x32_bf16 v[42:45], v[142:145], v[204:207], v[42:45]
	v_mfma_f32_16x16x32_bf16 v[38:41], v[134:137], v[212:215], v[38:41]
	v_mfma_f32_16x16x32_bf16 v[34:37], v[142:145], v[212:215], v[34:37]
	s_setprio 0
	s_setprio 1
	v_mfma_f32_16x16x32_bf16 v[30:33], v[146:149], v[180:183], v[30:33]
	v_mfma_f32_16x16x32_bf16 v[26:29], v[166:169], v[180:183], v[26:29]
	v_mfma_f32_16x16x32_bf16 v[22:25], v[146:149], v[190:193], v[22:25]
	v_mfma_f32_16x16x32_bf16 v[18:21], v[166:169], v[190:193], v[18:21]
	v_mfma_f32_16x16x32_bf16 v[14:17], v[146:149], v[200:203], v[14:17]
	v_mfma_f32_16x16x32_bf16 v[10:13], v[166:169], v[200:203], v[10:13]
	v_mfma_f32_16x16x32_bf16 v[6:9], v[146:149], v[208:211], v[6:9]
	v_mfma_f32_16x16x32_bf16 v[2:5], v[166:169], v[208:211], v[2:5]
	v_mfma_f32_16x16x32_bf16 v[30:33], v[162:165], v[186:189], v[30:33]
	v_mfma_f32_16x16x32_bf16 v[26:29], v[170:173], v[186:189], v[26:29]
	v_mfma_f32_16x16x32_bf16 v[22:25], v[162:165], v[196:199], v[22:25]
	v_mfma_f32_16x16x32_bf16 v[18:21], v[170:173], v[196:199], v[18:21]
	v_mfma_f32_16x16x32_bf16 v[14:17], v[162:165], v[204:207], v[14:17]
	v_mfma_f32_16x16x32_bf16 v[10:13], v[170:173], v[204:207], v[10:13]
	v_mfma_f32_16x16x32_bf16 v[6:9], v[162:165], v[212:215], v[6:9]
	v_mfma_f32_16x16x32_bf16 v[2:5], v[170:173], v[212:215], v[2:5]
	s_setprio 0
	s_barrier
	s_add_i32 s70, 0, 0x18000
	s_add_i32 s71, 0, 0x1c000
	v_add_u32_e32 v142, s70, v177
	v_add_u32_e32 v170, s71, v177
	ds_read_b128 v[130:133], v142
	ds_read_b128 v[134:137], v142 offset:1024
	ds_read_b128 v[138:141], v142 offset:2048
	ds_read_b128 v[142:145], v142 offset:3072
	ds_read_b128 v[146:149], v170
	ds_read_b128 v[162:165], v170 offset:1024
	ds_read_b128 v[166:169], v170 offset:2048
	ds_read_b128 v[170:173], v170 offset:3072
	s_add_u32 s26, s26, 0x4000
	s_addc_u32 s27, s27, 0
	s_mov_b32 m0, s55
	v_lshl_add_u64 v[174:175], s[26:27], 0, v[150:151]
	ds_read_b128 v[180:183], v184 offset:32768
	ds_read_b128 v[186:189], v184 offset:33792
	ds_read_b128 v[190:193], v184 offset:34816
	ds_read_b128 v[196:199], v184 offset:35840
	ds_read_b128 v[200:203], v184 offset:36864
	ds_read_b128 v[204:207], v184 offset:37888
	ds_read_b128 v[208:211], v184 offset:38912
	ds_read_b128 v[212:215], v184 offset:39936
	global_load_lds_dwordx4 v[174:175], off
	v_lshl_add_u64 v[174:175], s[26:27], 0, v[154:155]
	s_mov_b32 m0, s56
	s_nop 0
	global_load_lds_dwordx4 v[174:175], off
	s_waitcnt vmcnt(8)
	s_waitcnt lgkmcnt(0)
	s_barrier
	s_setprio 1
	s_waitcnt lgkmcnt(0)
	v_mfma_f32_16x16x32_bf16 v[126:129], v[130:133], v[180:183], v[126:129]
	v_mfma_f32_16x16x32_bf16 v[122:125], v[138:141], v[180:183], v[122:125]
	v_mfma_f32_16x16x32_bf16 v[118:121], v[130:133], v[190:193], v[118:121]
	v_mfma_f32_16x16x32_bf16 v[114:117], v[138:141], v[190:193], v[114:117]
	v_mfma_f32_16x16x32_bf16 v[110:113], v[130:133], v[200:203], v[110:113]
	v_mfma_f32_16x16x32_bf16 v[106:109], v[138:141], v[200:203], v[106:109]
	v_mfma_f32_16x16x32_bf16 v[102:105], v[130:133], v[208:211], v[102:105]
	v_mfma_f32_16x16x32_bf16 v[98:101], v[138:141], v[208:211], v[98:101]
	v_mfma_f32_16x16x32_bf16 v[126:129], v[134:137], v[186:189], v[126:129]
	v_mfma_f32_16x16x32_bf16 v[122:125], v[142:145], v[186:189], v[122:125]
	v_mfma_f32_16x16x32_bf16 v[118:121], v[134:137], v[196:199], v[118:121]
	v_mfma_f32_16x16x32_bf16 v[114:117], v[142:145], v[196:199], v[114:117]
	v_mfma_f32_16x16x32_bf16 v[110:113], v[134:137], v[204:207], v[110:113]
	v_mfma_f32_16x16x32_bf16 v[106:109], v[142:145], v[204:207], v[106:109]
	v_mfma_f32_16x16x32_bf16 v[102:105], v[134:137], v[212:215], v[102:105]
	v_mfma_f32_16x16x32_bf16 v[98:101], v[142:145], v[212:215], v[98:101]
	s_setprio 0
	s_setprio 1
	v_mfma_f32_16x16x32_bf16 v[94:97], v[146:149], v[180:183], v[94:97]
	v_mfma_f32_16x16x32_bf16 v[90:93], v[166:169], v[180:183], v[90:93]
	v_mfma_f32_16x16x32_bf16 v[86:89], v[146:149], v[190:193], v[86:89]
	v_mfma_f32_16x16x32_bf16 v[82:85], v[166:169], v[190:193], v[82:85]
	v_mfma_f32_16x16x32_bf16 v[78:81], v[146:149], v[200:203], v[78:81]
	v_mfma_f32_16x16x32_bf16 v[74:77], v[166:169], v[200:203], v[74:77]
	v_mfma_f32_16x16x32_bf16 v[70:73], v[146:149], v[208:211], v[70:73]
	v_mfma_f32_16x16x32_bf16 v[66:69], v[166:169], v[208:211], v[66:69]
	v_mfma_f32_16x16x32_bf16 v[94:97], v[162:165], v[186:189], v[94:97]
	v_mfma_f32_16x16x32_bf16 v[90:93], v[170:173], v[186:189], v[90:93]
	v_mfma_f32_16x16x32_bf16 v[86:89], v[162:165], v[196:199], v[86:89]
	v_mfma_f32_16x16x32_bf16 v[82:85], v[170:173], v[196:199], v[82:85]
	v_mfma_f32_16x16x32_bf16 v[78:81], v[162:165], v[204:207], v[78:81]
	v_mfma_f32_16x16x32_bf16 v[74:77], v[170:173], v[204:207], v[74:77]
	v_mfma_f32_16x16x32_bf16 v[70:73], v[162:165], v[212:215], v[70:73]
	v_mfma_f32_16x16x32_bf16 v[66:69], v[170:173], v[212:215], v[66:69]
	s_setprio 0
	s_barrier
; #define PG8_STAGE(bufoff, gbase, voff) do { _Pragma("unroll") for (int _i = 0; _i < 2; ++_i) \
;         __builtin_amdgcn_global_load_lds((const unsigned*)((const char*)(gbase) + (voff)[_i]), (PG8_LAS unsigned*)(lds + (bufoff) + ldsw + _i * 8192), 16, 0, 0); } while (0)
; #define PG8_LDA(dst, b, h) do { _Pragma("unroll") for (int m = 0; m < 4; ++m) _Pragma("unroll") for (int k = 0; k < 2; ++k) dst[m][k] = *(const PG8_LAS bf16x8*)(lds + PG8_SA(b, h) + aoff + m * 2048 + k * 1024); } while (0)
; #define PG8_MMA(ai, bj, At, Bt) do { __builtin_amdgcn_s_setprio(1); _Pragma("unroll") for (int m = 0; m < 4; ++m) _Pragma("unroll") for (int n = 0; n < 2; ++n) _Pragma("unroll") for (int k = 0; k < 2; ++k) \
;         acc[ai][bj][m][n] = __builtin_amdgcn_mfma_f32_16x16x32_bf16(Bt[n][k], At[m][k], acc[ai][bj][m][n], 0, 0, 0); __builtin_amdgcn_s_setprio(0); } while (0)
; #define PG8_WAIT_V(n) asm volatile("s_waitcnt vmcnt(" #n ")" ::: "memory")
; #define PG8_WAIT_L(n) asm volatile("s_waitcnt lgkmcnt(" #n ")" ::: "memory")
; #define PG8_BAR __builtin_amdgcn_s_barrier()
; #define PG8_SCHED __builtin_amdgcn_sched_barrier(0)
; #define GAS __attribute__((address_space(1)))
; __device__ __forceinline__ size_t TX(int row, int col) { return ((((size_t)(row >> 8) * 16 + (col >> 6)) * 256 + (row & 255)) << 6) + (col & 63); }
; template <class Epi, class Sched, bool ALIGN_EPI = false, bool SP2 = false, bool ATILED = false, bool BTILED = false>
; __device__ __forceinline__ void gemm_phase(PG8_LAS unsigned char* lds, const Gemm g, const Sched& S, const Epi& E, const int tid) {
;     ...
;             PG8_WAIT_V(8); PG8_WAIT_L(0); PG8_BAR; PG8_MMA(0, 0, At, B0); PG8_MMA(0, 1, At, B1); PG8_BAR; PG8_SCHED;
;             PG8_LDA(At, 1, 1); PG8_STAGE(PG8_SB(1, 0), b3, voffB); PG8_STAGE(PG8_SB(1, 1), b3 + hstepB, voffB); PG8_STAGE(PG8_SA(1, 0), a3, voffA);
;             PG8_WAIT_V(8); PG8_WAIT_L(0); PG8_BAR; PG8_MMA(1, 0, At, B0); PG8_MMA(1, 1, At, B1); PG8_BAR; PG8_SCHED;
;     __device__ __forceinline__ void operator()(const f32x4 (&acc)[2][2][4][2], const pg8::Unit& u, int wr, int wc, int fr, int fq) const {
;     ...
;                 for (int m = 0; m < 4; ++m) xr[m] = *(const GAS u32x4*)(xres + TX(row0 + 128 * ai + 16 * m, col));
; #pragma unroll
;                 for (int n = 0; n < 2; ++n) ga4[n] = *(const GAS f32x4*)(ga + col + 4 * n);
	s_add_u32 s26, s24, 0x8000
	s_addc_u32 s27, s25, 0
	s_add_i32 s70, s70, s52
	v_lshl_add_u64 v[174:175], s[26:27], 0, v[152:153]
	s_mov_b32 m0, s70
	ds_read_b128 v[180:183], v184 offset:49152
	ds_read_b128 v[186:189], v184 offset:50176
	ds_read_b128 v[190:193], v184 offset:51200
	ds_read_b128 v[196:199], v184 offset:52224
	ds_read_b128 v[200:203], v184 offset:53248
	ds_read_b128 v[204:207], v184 offset:54272
	ds_read_b128 v[208:211], v184 offset:55296
	ds_read_b128 v[212:215], v184 offset:56320
	global_load_lds_dwordx4 v[174:175], off
	s_add_i32 m0, s70, 0x2000
	s_add_u32 s24, s24, 0xc000
	v_lshl_add_u64 v[174:175], s[26:27], 0, v[156:157]
	s_addc_u32 s25, s25, 0
	s_add_i32 s26, s71, s52
	global_load_lds_dwordx4 v[174:175], off
	v_lshl_add_u64 v[174:175], s[24:25], 0, v[152:153]
	s_mov_b32 m0, s26
	s_nop 0
	global_load_lds_dwordx4 v[174:175], off
	v_lshl_add_u64 v[174:175], s[24:25], 0, v[156:157]
	s_add_i32 m0, s26, 0x2000
	s_nop 0
	global_load_lds_dwordx4 v[174:175], off
	v_lshl_add_u64 v[174:175], s[18:19], 0, v[150:151]
	s_mov_b32 m0, s58
	s_nop 0
	global_load_lds_dwordx4 v[174:175], off
	v_lshl_add_u64 v[174:175], s[18:19], 0, v[154:155]
	s_mov_b32 m0, s59
	s_nop 0
	global_load_lds_dwordx4 v[174:175], off
	s_waitcnt vmcnt(8)
	s_cmp_lg_u32 s69, 40
	s_cbranch_scc1 .Ldn_touch_skip
	s_lshl_b32 s98, s65, 4
	s_lshl_b32 s99, s66, 2
	s_add_i32 s98, s98, s99
	s_lshr_b32 s99, s57, 6
	s_add_i32 s98, s98, s99
	s_lshl_b32 s98, s98, 15
	s_lshl_b32 s99, s30, 7
	s_add_i32 s98, s98, s99
	s_and_b32 s99, s57, 63
	s_lshl_b32 s99, s99, 1
	s_add_i32 s98, s98, s99
	v_lshlrev_b32_e32 v253, 7, v1
	v_lshl_add_u32 v253, v176, 1, v253
	v_add_u32_e32 v253, s98, v253
	global_load_dword v231, v253, s[20:21]
	global_load_dword v231, v253, s[20:21] offset:2048
	v_add_u32_e32 v253, 0x1000, v253
	global_load_dword v231, v253, s[20:21]
	global_load_dword v231, v253, s[20:21] offset:2048
	v_add_u32_e32 v253, 0x3000, v253
	global_load_dword v231, v253, s[20:21]
	global_load_dword v231, v253, s[20:21] offset:2048
	v_add_u32_e32 v253, 0x1000, v253
	global_load_dword v231, v253, s[20:21]
	global_load_dword v231, v253, s[20:21] offset:2048
	v_add_u32_e32 v253, 0xb000, v253
	global_load_dword v231, v253, s[20:21]
	global_load_dword v231, v253, s[20:21] offset:2048
	v_add_u32_e32 v253, 0x1000, v253
	global_load_dword v231, v253, s[20:21]
	global_load_dword v231, v253, s[20:21] offset:2048
	v_add_u32_e32 v253, 0x3000, v253
	global_load_dword v231, v253, s[20:21]
	global_load_dword v231, v253, s[20:21] offset:2048
	v_add_u32_e32 v253, 0x1000, v253
	global_load_dword v231, v253, s[20:21]
	global_load_dword v231, v253, s[20:21] offset:2048
	s_lshl_b32 s98, s66, 10
	s_lshl_b32 s99, s57, 2
	s_add_i32 s98, s98, s99
	v_lshl_add_u32 v253, v176, 2, s98
	global_load_dword v231, v253, s[6:7]
	global_load_dword v231, v253, s[6:7] offset:512
.Ldn_touch_skip:
	s_waitcnt lgkmcnt(0)
	s_barrier
	s_setprio 1
	s_waitcnt lgkmcnt(0)
	v_mfma_f32_16x16x32_bf16 v[62:65], v[130:133], v[180:183], v[62:65]
	v_mfma_f32_16x16x32_bf16 v[58:61], v[138:141], v[180:183], v[58:61]
	v_mfma_f32_16x16x32_bf16 v[54:57], v[130:133], v[190:193], v[54:57]
	v_mfma_f32_16x16x32_bf16 v[50:53], v[138:141], v[190:193], v[50:53]
	v_mfma_f32_16x16x32_bf16 v[46:49], v[130:133], v[200:203], v[46:49]
	v_mfma_f32_16x16x32_bf16 v[42:45], v[138:141], v[200:203], v[42:45]
	v_mfma_f32_16x16x32_bf16 v[38:41], v[130:133], v[208:211], v[38:41]
	v_mfma_f32_16x16x32_bf16 v[34:37], v[138:141], v[208:211], v[34:37]
	v_mfma_f32_16x16x32_bf16 v[62:65], v[134:137], v[186:189], v[62:65]
	v_mfma_f32_16x16x32_bf16 v[58:61], v[142:145], v[186:189], v[58:61]
	v_mfma_f32_16x16x32_bf16 v[54:57], v[134:137], v[196:199], v[54:57]
	v_mfma_f32_16x16x32_bf16 v[50:53], v[142:145], v[196:199], v[50:53]
	v_mfma_f32_16x16x32_bf16 v[46:49], v[134:137], v[204:207], v[46:49]
	v_mfma_f32_16x16x32_bf16 v[42:45], v[142:145], v[204:207], v[42:45]
	v_mfma_f32_16x16x32_bf16 v[38:41], v[134:137], v[212:215], v[38:41]
	v_mfma_f32_16x16x32_bf16 v[34:37], v[142:145], v[212:215], v[34:37]
	s_setprio 0
	s_setprio 1
	v_mfma_f32_16x16x32_bf16 v[30:33], v[146:149], v[180:183], v[30:33]
	v_mfma_f32_16x16x32_bf16 v[26:29], v[166:169], v[180:183], v[26:29]
	v_mfma_f32_16x16x32_bf16 v[22:25], v[146:149], v[190:193], v[22:25]
	v_mfma_f32_16x16x32_bf16 v[18:21], v[166:169], v[190:193], v[18:21]
	v_mfma_f32_16x16x32_bf16 v[14:17], v[146:149], v[200:203], v[14:17]
	v_mfma_f32_16x16x32_bf16 v[10:13], v[166:169], v[200:203], v[10:13]
	v_mfma_f32_16x16x32_bf16 v[6:9], v[146:149], v[208:211], v[6:9]
	v_mfma_f32_16x16x32_bf16 v[2:5], v[166:169], v[208:211], v[2:5]
	v_mfma_f32_16x16x32_bf16 v[30:33], v[162:165], v[186:189], v[30:33]
	v_mfma_f32_16x16x32_bf16 v[26:29], v[170:173], v[186:189], v[26:29]
	v_mfma_f32_16x16x32_bf16 v[22:25], v[162:165], v[196:199], v[22:25]
	v_mfma_f32_16x16x32_bf16 v[18:21], v[170:173], v[196:199], v[18:21]
	v_mfma_f32_16x16x32_bf16 v[14:17], v[162:165], v[204:207], v[14:17]
	v_mfma_f32_16x16x32_bf16 v[10:13], v[170:173], v[204:207], v[10:13]
	v_mfma_f32_16x16x32_bf16 v[6:9], v[162:165], v[212:215], v[6:9]
	v_mfma_f32_16x16x32_bf16 v[2:5], v[170:173], v[212:215], v[2:5]
	s_setprio 0
	s_barrier
	s_add_i32 s69, s69, 2
	s_add_u32 s16, s16, 0x10000
	s_addc_u32 s17, s17, 0
	s_add_u32 s67, s67, 0x10000
	s_addc_u32 s68, s68, 0
	s_cmp_gt_u32 s69, 41
	s_cbranch_scc0 .LBB0_478
	s_and_b64 vcc, exec, s[12:13]
	s_cbranch_vccz .LBB0_481
	s_barrier
